# grid barrier: all blocks poll the global generation word (per-XCD forwarding hop removed; leaders no longer bump the per-XCD word)
# speedup vs baseline: 1.0059x; 1.0047x over previous
; __device__ __forceinline__ unsigned xb_ld(unsigned* p) { return __hip_atomic_load(p, __ATOMIC_RELAXED, __HIP_MEMORY_SCOPE_AGENT); }
; __device__ __forceinline__ unsigned xb_add(unsigned* p, unsigned v) { return __hip_atomic_fetch_add(p, v, __ATOMIC_RELAXED, __HIP_MEMORY_SCOPE_AGENT); }
; __device__ __forceinline__ void grid_barrier(unsigned* bar, volatile unsigned* st) {
;     ...
;       __builtin_amdgcn_fence(__ATOMIC_RELEASE, "agent");
;       asm volatile("s_waitcnt vmcnt(0)" ::: "memory");
;       const unsigned og = xb_add(&bar[XB_TOP], 1u);
;       const unsigned tg = og / nx;
;       if (og + 1u == (tg + 1u) * nx) xb_add(&bar[XB_TOPGEN], 1u);
;       else { while (xb_ld(&bar[XB_TOPGEN]) == tg) __builtin_amdgcn_s_sleep(1); }
;       __builtin_amdgcn_fence(__ATOMIC_ACQUIRE, "agent");
;       xb_add(&bar[XB_XGEN(x)], 1u);
;       asm volatile("s_waitcnt vmcnt(0)" ::: "memory");
.LBB0_6:
	s_or_b64 exec, exec, s[6:7]
	v_readlane_b32 s6, v253, 3
	v_readlane_b32 s7, v253, 4
	s_waitcnt vmcnt(0)
	buffer_inv sc1
	s_waitcnt vmcnt(0)

; __device__ __forceinline__ unsigned xb_ld(unsigned* p) { return __hip_atomic_load(p, __ATOMIC_RELAXED, __HIP_MEMORY_SCOPE_AGENT); }
; __device__ __forceinline__ unsigned xb_add(unsigned* p, unsigned v) { return __hip_atomic_fetch_add(p, v, __ATOMIC_RELAXED, __HIP_MEMORY_SCOPE_AGENT); }
; __device__ __forceinline__ void grid_barrier(unsigned* bar, volatile unsigned* st) {
;     ...
;   if (threadIdx.x == 0) {
;     __builtin_amdgcn_s_waitcnt(0);
;     const unsigned x = st[2], nloc = st[0], nx = st[1];
;     const unsigned old = xb_add(&bar[XB_XSUB(x)], 1u);
;     const unsigned gen = old / nloc;
;     if (old + 1u == (gen + 1u) * nloc) {
;       __builtin_amdgcn_fence(__ATOMIC_RELEASE, "agent");
;       asm volatile("s_waitcnt vmcnt(0)" ::: "memory");
;       const unsigned og = xb_add(&bar[XB_TOP], 1u);
;       const unsigned tg = og / nx;
;       if (og + 1u == (tg + 1u) * nx) xb_add(&bar[XB_TOPGEN], 1u);
;       else { while (xb_ld(&bar[XB_TOPGEN]) == tg) __builtin_amdgcn_s_sleep(1); }
;       __builtin_amdgcn_fence(__ATOMIC_ACQUIRE, "agent");
;       xb_add(&bar[XB_XGEN(x)], 1u);
;       asm volatile("s_waitcnt vmcnt(0)" ::: "memory");
;     } else {
;       while (xb_ld(&bar[XB_XGEN(x)]) == gen) __builtin_amdgcn_s_sleep(1);
;       __builtin_amdgcn_fence(__ATOMIC_ACQUIRE, "agent");
;       asm volatile("s_waitcnt vmcnt(0)" ::: "memory");
;     }
.LBB0_882:
	v_mov_b32_e32 v6, 0x24000
	s_waitcnt vmcnt(0) expcnt(0) lgkmcnt(0)
	ds_read_b32 v2, v6 offset:8
	ds_read_b32 v4, v6
	ds_read_b32 v0, v6 offset:4
	s_waitcnt lgkmcnt(0)
	v_readlane_b32 s6, v253, 3
	v_readlane_b32 s7, v253, 4
	s_waitcnt lgkmcnt(0)
	v_lshlrev_b32_e32 v1, 6, v2
	v_add_u32_e32 v200, 0x500, v1
	v_lshl_add_u64 v[2:3], v[200:201], 2, s[6:7]
	global_atomic_add v3, v[2:3], v238, off sc0
	v_add_u32_e32 v200, 0x900, v1
	v_cvt_f32_u32_e32 v2, v4
	v_sub_u32_e32 v5, 0, v4
	v_rcp_iflag_f32_e32 v2, v2
	s_nop 0
	v_mul_f32_e32 v2, 0x4f7ffffe, v2
	v_cvt_u32_f32_e32 v2, v2
	v_mul_lo_u32 v5, v5, v2
	v_mul_hi_u32 v5, v2, v5
	v_add_u32_e32 v2, v2, v5
	s_waitcnt vmcnt(0)
	v_mul_hi_u32 v2, v3, v2
	v_mul_lo_u32 v5, v2, v4
	v_sub_u32_e32 v5, v3, v5
	v_cmp_ge_u32_e32 vcc, v5, v4
	v_add_u32_e32 v6, 1, v2
	v_add_u32_e32 v3, 1, v3
	v_cndmask_b32_e32 v2, v2, v6, vcc
	v_sub_u32_e32 v6, v5, v4
	v_cndmask_b32_e32 v5, v5, v6, vcc
	v_cmp_ge_u32_e32 vcc, v5, v4
	v_add_u32_e32 v5, 1, v2
	s_nop 0
	v_cndmask_b32_e32 v2, v2, v5, vcc
	v_mad_u64_u32 v[4:5], s[6:7], v4, v2, v[4:5]
	v_cmp_ne_u32_e32 vcc, v3, v4
	s_and_saveexec_b64 s[6:7], vcc
	s_xor_b64 s[6:7], exec, s[6:7]
	s_cbranch_execz .LBB0_887
	v_readlane_b32 s8, v253, 3
	v_readlane_b32 s9, v253, 4
	s_nop 1
	s_add_u32 s8, s8, 0x3500
	s_addc_u32 s9, s9, 0
	v_mov_b32_e32 v0, s8
	v_mov_b32_e32 v1, s9
	global_load_dword v3, v[0:1], off sc1
	s_waitcnt vmcnt(0)
	v_cmp_eq_u32_e32 vcc, v3, v2
	s_and_saveexec_b64 s[8:9], vcc
	s_cbranch_execz .LBB0_886
	s_mov_b64 s[10:11], 0
